# P0: x->bf16 conversion loop unrolled 4x and software-pipelined (8 x 16 B loads per lane in flight, counted vmcnt, stores no longer gate the next loads)
# baseline (speedup 1.0000x reference)
; __device__ __forceinline__ unsigned cvtpk(float lo, float hi) { f32x2_t v = {lo, hi}; bf16x2_t b = __builtin_convertvector(v, bf16x2_t); return __builtin_bit_cast(unsigned, b); }
; __global__ void __launch_bounds__(NTHREADS, 2) fwd_megakernel(Args args) {
;     ...
;         const size_t n8 = (size_t)MTOK * DM / 8;
;         for (size_t i = gt; i < n8; i += NGT) { const f32x4 a = *(const f32x4*)(x + i * 8), c = *(const f32x4*)(x + i * 8 + 4);
;             v4u o; o.x = cvtpk(a[0], a[1]); o.y = cvtpk(a[2], a[3]); o.z = cvtpk(c[0], c[1]); o.w = cvtpk(c[2], c[3]); *(v4u*)(XB + i * 8) = o; }
.LBB0_43:
	s_or_b64 exec, exec, s[0:1]
	s_waitcnt lgkmcnt(0)
	s_ashr_i32 s15, s42, 31
	s_mov_b32 s14, s42
	s_mov_b64 s[0:1], 0x800000
	s_lshl_b64 s[24:25], s[14:15], 9
	v_cmp_gt_u64_e32 vcc, s[0:1], v[4:5]
	s_and_saveexec_b64 s[0:1], vcc
	s_cbranch_execz .LBB0_46
	s_lshl_b64 s[4:5], s[2:3], 14
	s_add_u32 s4, s12, s4
	v_lshlrev_b64 v[6:7], 5, v[2:3]
	s_addc_u32 s5, s13, s5
	v_lshl_add_u64 v[6:7], s[4:5], 0, v[6:7]
	s_lshl_b64 s[4:5], s[14:15], 14
	s_lshl_b64 s[8:9], s[2:3], 13
	s_add_u32 s8, s40, s8
	s_addc_u32 s9, s41, s9
	v_lshl_add_u64 v[2:3], v[2:3], 4, s[8:9]
	s_mov_b64 s[8:9], 0x7c00000
	v_lshl_add_u64 v[6:7], v[6:7], 0, 16
	v_lshl_add_u64 v[2:3], v[2:3], 0, s[8:9]
	s_lshl_b64 s[8:9], s[14:15], 13
	s_mov_b64 s[10:11], 0
	s_mov_b64 s[18:19], 0x7fffff
	s_cmp_lg_u32 s42, 0x100
	s_cbranch_scc1 .LBB0_45
	s_mov_b32 s10, 7
	global_load_dwordx4 v[20:23], v[6:7], off offset:-16
	global_load_dwordx4 v[24:27], v[6:7], off
	v_lshl_add_u64 v[16:17], v[6:7], 0, s[4:5]
	global_load_dwordx4 v[28:31], v[16:17], off offset:-16
	global_load_dwordx4 v[32:35], v[16:17], off
	v_lshl_add_u64 v[16:17], v[16:17], 0, s[4:5]
	global_load_dwordx4 v[36:39], v[16:17], off offset:-16
	global_load_dwordx4 v[40:43], v[16:17], off
	v_lshl_add_u64 v[16:17], v[16:17], 0, s[4:5]
	global_load_dwordx4 v[44:47], v[16:17], off offset:-16
	global_load_dwordx4 v[48:51], v[16:17], off
	v_lshl_add_u64 v[6:7], v[16:17], 0, s[4:5]
	global_load_dwordx4 v[52:55], v[6:7], off offset:-16
	global_load_dwordx4 v[56:59], v[6:7], off
	v_lshl_add_u64 v[16:17], v[6:7], 0, s[4:5]
	global_load_dwordx4 v[60:63], v[16:17], off offset:-16
	global_load_dwordx4 v[64:67], v[16:17], off
	v_lshl_add_u64 v[16:17], v[16:17], 0, s[4:5]
	global_load_dwordx4 v[68:71], v[16:17], off offset:-16
	global_load_dwordx4 v[72:75], v[16:17], off
	v_lshl_add_u64 v[16:17], v[16:17], 0, s[4:5]
	global_load_dwordx4 v[76:79], v[16:17], off offset:-16
	global_load_dwordx4 v[80:83], v[16:17], off
	v_lshl_add_u64 v[6:7], v[16:17], 0, s[4:5]
	s_waitcnt vmcnt(14)
	v_cvt_pk_bf16_f32 v20, v20, v21
	v_cvt_pk_bf16_f32 v21, v22, v23
	v_cvt_pk_bf16_f32 v22, v24, v25
	v_cvt_pk_bf16_f32 v23, v26, v27
	global_store_dwordx4 v[2:3], v[20:23], off
	v_lshl_add_u64 v[2:3], v[2:3], 0, s[8:9]
	s_waitcnt vmcnt(13)
	v_cvt_pk_bf16_f32 v28, v28, v29
	v_cvt_pk_bf16_f32 v29, v30, v31
	v_cvt_pk_bf16_f32 v30, v32, v33
	v_cvt_pk_bf16_f32 v31, v34, v35
	global_store_dwordx4 v[2:3], v[28:31], off
	v_lshl_add_u64 v[2:3], v[2:3], 0, s[8:9]
	s_waitcnt vmcnt(12)
	v_cvt_pk_bf16_f32 v36, v36, v37
	v_cvt_pk_bf16_f32 v37, v38, v39
	v_cvt_pk_bf16_f32 v38, v40, v41
	v_cvt_pk_bf16_f32 v39, v42, v43
	global_store_dwordx4 v[2:3], v[36:39], off
	v_lshl_add_u64 v[2:3], v[2:3], 0, s[8:9]
	s_waitcnt vmcnt(11)
	v_cvt_pk_bf16_f32 v44, v44, v45
	v_cvt_pk_bf16_f32 v45, v46, v47
	v_cvt_pk_bf16_f32 v46, v48, v49
	v_cvt_pk_bf16_f32 v47, v50, v51
	global_store_dwordx4 v[2:3], v[44:47], off
	v_lshl_add_u64 v[2:3], v[2:3], 0, s[8:9]
; __device__ __forceinline__ unsigned cvtpk(float lo, float hi) { f32x2_t v = {lo, hi}; bf16x2_t b = __builtin_convertvector(v, bf16x2_t); return __builtin_bit_cast(unsigned, b); }
; __global__ void __launch_bounds__(NTHREADS, 2) fwd_megakernel(Args args) {
;     ...
;         const size_t n8 = (size_t)MTOK * DM / 8;
;         for (size_t i = gt; i < n8; i += NGT) { const f32x4 a = *(const f32x4*)(x + i * 8), c = *(const f32x4*)(x + i * 8 + 4);
;             v4u o; o.x = cvtpk(a[0], a[1]); o.y = cvtpk(a[2], a[3]); o.z = cvtpk(c[0], c[1]); o.w = cvtpk(c[2], c[3]); *(v4u*)(XB + i * 8) = o; }
.Lxcvt_loop:
	global_load_dwordx4 v[20:23], v[6:7], off offset:-16
	global_load_dwordx4 v[24:27], v[6:7], off
	v_lshl_add_u64 v[16:17], v[6:7], 0, s[4:5]
	global_load_dwordx4 v[28:31], v[16:17], off offset:-16
	global_load_dwordx4 v[32:35], v[16:17], off
	v_lshl_add_u64 v[16:17], v[16:17], 0, s[4:5]
	global_load_dwordx4 v[36:39], v[16:17], off offset:-16
	global_load_dwordx4 v[40:43], v[16:17], off
	v_lshl_add_u64 v[16:17], v[16:17], 0, s[4:5]
	global_load_dwordx4 v[44:47], v[16:17], off offset:-16
	global_load_dwordx4 v[48:51], v[16:17], off
	v_lshl_add_u64 v[6:7], v[16:17], 0, s[4:5]
	s_waitcnt vmcnt(18)
	v_cvt_pk_bf16_f32 v52, v52, v53
	v_cvt_pk_bf16_f32 v53, v54, v55
	v_cvt_pk_bf16_f32 v54, v56, v57
	v_cvt_pk_bf16_f32 v55, v58, v59
	global_store_dwordx4 v[2:3], v[52:55], off
	v_lshl_add_u64 v[2:3], v[2:3], 0, s[8:9]
	s_waitcnt vmcnt(17)
	v_cvt_pk_bf16_f32 v60, v60, v61
	v_cvt_pk_bf16_f32 v61, v62, v63
	v_cvt_pk_bf16_f32 v62, v64, v65
	v_cvt_pk_bf16_f32 v63, v66, v67
	global_store_dwordx4 v[2:3], v[60:63], off
	v_lshl_add_u64 v[2:3], v[2:3], 0, s[8:9]
	s_waitcnt vmcnt(16)
	v_cvt_pk_bf16_f32 v68, v68, v69
	v_cvt_pk_bf16_f32 v69, v70, v71
	v_cvt_pk_bf16_f32 v70, v72, v73
	v_cvt_pk_bf16_f32 v71, v74, v75
	global_store_dwordx4 v[2:3], v[68:71], off
	v_lshl_add_u64 v[2:3], v[2:3], 0, s[8:9]
	s_waitcnt vmcnt(15)
	v_cvt_pk_bf16_f32 v76, v76, v77
	v_cvt_pk_bf16_f32 v77, v78, v79
	v_cvt_pk_bf16_f32 v78, v80, v81
	v_cvt_pk_bf16_f32 v79, v82, v83
	global_store_dwordx4 v[2:3], v[76:79], off
	v_lshl_add_u64 v[2:3], v[2:3], 0, s[8:9]
	global_load_dwordx4 v[52:55], v[6:7], off offset:-16
	global_load_dwordx4 v[56:59], v[6:7], off
	v_lshl_add_u64 v[16:17], v[6:7], 0, s[4:5]
	global_load_dwordx4 v[60:63], v[16:17], off offset:-16
	global_load_dwordx4 v[64:67], v[16:17], off
	v_lshl_add_u64 v[16:17], v[16:17], 0, s[4:5]
	global_load_dwordx4 v[68:71], v[16:17], off offset:-16
	global_load_dwordx4 v[72:75], v[16:17], off
	v_lshl_add_u64 v[16:17], v[16:17], 0, s[4:5]
	global_load_dwordx4 v[76:79], v[16:17], off offset:-16
	global_load_dwordx4 v[80:83], v[16:17], off
	v_lshl_add_u64 v[6:7], v[16:17], 0, s[4:5]
	s_waitcnt vmcnt(18)
	v_cvt_pk_bf16_f32 v20, v20, v21
	v_cvt_pk_bf16_f32 v21, v22, v23
	v_cvt_pk_bf16_f32 v22, v24, v25
	v_cvt_pk_bf16_f32 v23, v26, v27
	global_store_dwordx4 v[2:3], v[20:23], off
	v_lshl_add_u64 v[2:3], v[2:3], 0, s[8:9]
	s_waitcnt vmcnt(17)
	v_cvt_pk_bf16_f32 v28, v28, v29
	v_cvt_pk_bf16_f32 v29, v30, v31
	v_cvt_pk_bf16_f32 v30, v32, v33
	v_cvt_pk_bf16_f32 v31, v34, v35
	global_store_dwordx4 v[2:3], v[28:31], off
	v_lshl_add_u64 v[2:3], v[2:3], 0, s[8:9]
	s_waitcnt vmcnt(16)
	v_cvt_pk_bf16_f32 v36, v36, v37
	v_cvt_pk_bf16_f32 v37, v38, v39
	v_cvt_pk_bf16_f32 v38, v40, v41
	v_cvt_pk_bf16_f32 v39, v42, v43
	global_store_dwordx4 v[2:3], v[36:39], off
	v_lshl_add_u64 v[2:3], v[2:3], 0, s[8:9]
	s_waitcnt vmcnt(15)
	v_cvt_pk_bf16_f32 v44, v44, v45
	v_cvt_pk_bf16_f32 v45, v46, v47
	v_cvt_pk_bf16_f32 v46, v48, v49
	v_cvt_pk_bf16_f32 v47, v50, v51
	global_store_dwordx4 v[2:3], v[44:47], off
	v_lshl_add_u64 v[2:3], v[2:3], 0, s[8:9]
	s_add_i32 s10, s10, -1
	s_cmp_lg_u32 s10, 0
	s_cbranch_scc1 .Lxcvt_loop
	s_waitcnt vmcnt(10)
	v_cvt_pk_bf16_f32 v52, v52, v53
	v_cvt_pk_bf16_f32 v53, v54, v55
	v_cvt_pk_bf16_f32 v54, v56, v57
	v_cvt_pk_bf16_f32 v55, v58, v59
	global_store_dwordx4 v[2:3], v[52:55], off
	v_lshl_add_u64 v[2:3], v[2:3], 0, s[8:9]
	s_waitcnt vmcnt(9)
	v_cvt_pk_bf16_f32 v60, v60, v61
	v_cvt_pk_bf16_f32 v61, v62, v63
	v_cvt_pk_bf16_f32 v62, v64, v65
	v_cvt_pk_bf16_f32 v63, v66, v67
	global_store_dwordx4 v[2:3], v[60:63], off
	v_lshl_add_u64 v[2:3], v[2:3], 0, s[8:9]
	s_waitcnt vmcnt(8)
	v_cvt_pk_bf16_f32 v68, v68, v69
	v_cvt_pk_bf16_f32 v69, v70, v71
	v_cvt_pk_bf16_f32 v70, v72, v73
	v_cvt_pk_bf16_f32 v71, v74, v75
	global_store_dwordx4 v[2:3], v[68:71], off
	v_lshl_add_u64 v[2:3], v[2:3], 0, s[8:9]
	s_waitcnt vmcnt(7)
	v_cvt_pk_bf16_f32 v76, v76, v77
	v_cvt_pk_bf16_f32 v77, v78, v79
	v_cvt_pk_bf16_f32 v78, v80, v81
	v_cvt_pk_bf16_f32 v79, v82, v83
	global_store_dwordx4 v[2:3], v[76:79], off
	v_lshl_add_u64 v[2:3], v[2:3], 0, s[8:9]
	s_branch .LBB0_46
